# HGRN pass1/pass2 u16 loads without the nt hint
# baseline (speedup 1.0000x reference)
.LBB0_328:
	v_mov_b32 v9, v145
	s_lshl_b32 s34, s10, 7
	v_readfirstlane_b32 s37, v9
	s_ashr_i32 s36, s37, 7
	s_lshl_b32 s11, s36, 4
	s_and_b32 s13, s34, 0xfffffc00
	s_or_b32 s14, s34, 0x3ff
	s_or_b32 s15, s11, 14
	s_or_b32 s4, s11, 15
	s_and_b32 s12, s10, 1
	s_sub_i32 s16, s14, s15
	s_sub_i32 s17, s14, s4
	s_add_i32 s18, s4, s13
	s_cmp_eq_u32 s12, 0
	s_cselect_b64 s[4:5], -1, 0
	s_and_b64 s[4:5], s[4:5], exec
	s_cselect_b32 s39, s18, s17
	s_add_i32 s15, s15, s13
	s_cmp_eq_u32 s12, 0
	s_cselect_b64 s[4:5], -1, 0
	s_and_b64 s[4:5], s[4:5], exec
	s_cselect_b32 s40, s15, s16
	s_or_b32 s4, s11, 13
	s_sub_i32 s15, s14, s4
	s_add_i32 s16, s4, s13
	s_cmp_eq_u32 s12, 0
	s_cselect_b64 s[4:5], -1, 0
	s_and_b64 s[4:5], s[4:5], exec
	s_cselect_b32 s41, s16, s15
	s_or_b32 s4, s11, 12
	s_sub_i32 s15, s14, s4
	s_add_i32 s16, s4, s13
	s_cmp_eq_u32 s12, 0
	s_cselect_b64 s[4:5], -1, 0
	s_and_b64 s[4:5], s[4:5], exec
	s_cselect_b32 s42, s16, s15
	s_or_b32 s4, s11, 11
	s_sub_i32 s15, s14, s4
	s_add_i32 s16, s4, s13
	s_cmp_eq_u32 s12, 0
	s_cselect_b64 s[4:5], -1, 0
	s_and_b64 s[4:5], s[4:5], exec
	s_cselect_b32 s43, s16, s15
	s_or_b32 s4, s11, 10
	s_sub_i32 s15, s14, s4
	s_add_i32 s16, s4, s13
	s_cmp_eq_u32 s12, 0
	s_cselect_b64 s[4:5], -1, 0
	s_and_b64 s[4:5], s[4:5], exec
	s_cselect_b32 s48, s16, s15
	s_or_b32 s4, s11, 9
	s_sub_i32 s15, s14, s4
	s_add_i32 s16, s4, s13
	s_cmp_eq_u32 s12, 0
	s_cselect_b64 s[4:5], -1, 0
	s_and_b64 s[4:5], s[4:5], exec
	s_cselect_b32 s46, s16, s15
	s_or_b32 s4, s11, 8
	s_sub_i32 s15, s14, s4
	s_add_i32 s16, s4, s13
	s_cmp_eq_u32 s12, 0
	s_cselect_b64 s[4:5], -1, 0
	s_and_b64 s[4:5], s[4:5], exec
	s_cselect_b32 s44, s16, s15
	s_or_b32 s4, s11, 7
	s_sub_i32 s15, s14, s4
	s_add_i32 s16, s4, s13
	s_cmp_eq_u32 s12, 0
	s_cselect_b64 s[4:5], -1, 0
	s_and_b64 s[4:5], s[4:5], exec
	s_cselect_b32 s26, s16, s15
	s_or_b32 s4, s11, 6
	s_sub_i32 s15, s14, s4
	s_add_i32 s16, s4, s13
	s_cmp_eq_u32 s12, 0
	s_cselect_b64 s[4:5], -1, 0
	s_and_b64 s[4:5], s[4:5], exec
	s_cselect_b32 s24, s16, s15
	s_or_b32 s4, s11, 5
	s_sub_i32 s15, s14, s4
	s_add_i32 s16, s4, s13
	s_cmp_eq_u32 s12, 0
	s_cselect_b64 s[4:5], -1, 0
	s_and_b64 s[4:5], s[4:5], exec
	s_cselect_b32 s22, s16, s15
	s_or_b32 s4, s11, 4
	s_sub_i32 s15, s14, s4
	s_add_i32 s16, s4, s13
	s_cmp_eq_u32 s12, 0
	s_cselect_b64 s[4:5], -1, 0
	s_and_b64 s[4:5], s[4:5], exec
	s_cselect_b32 s20, s16, s15
	s_or_b32 s4, s11, 3
	s_sub_i32 s15, s14, s4
	s_add_i32 s16, s4, s13
	s_cmp_eq_u32 s12, 0
	s_cselect_b64 s[4:5], -1, 0
	s_and_b64 s[4:5], s[4:5], exec
	s_cselect_b32 s18, s16, s15
	s_or_b32 s4, s11, 2
	s_sub_i32 s15, s14, s4
	s_add_i32 s16, s4, s13
	s_cmp_eq_u32 s12, 0
	s_cselect_b64 s[4:5], -1, 0
	s_and_b64 s[4:5], s[4:5], exec
	s_cselect_b32 s16, s16, s15
	s_or_b32 s4, s11, 1
	s_sub_i32 s15, s14, s4
	s_add_i32 s17, s4, s13
	s_cmp_eq_u32 s12, 0
	s_cselect_b64 s[4:5], -1, 0
	s_and_b64 s[4:5], s[4:5], exec
	s_cselect_b32 s15, s17, s15
	s_sub_i32 s38, s14, s11
	s_add_i32 s11, s11, s13
	s_cmp_eq_u32 s12, 0
	s_cselect_b64 s[12:13], -1, 0
	s_and_b64 s[4:5], s[12:13], exec
	s_cselect_b32 s4, s60, s62
	s_cselect_b32 s5, s61, s63
	s_cselect_b32 s14, 0x200, s2
	s_cselect_b32 s17, s11, s38
	s_lshl_b32 s19, s10, 6
	v_and_b32_e32 v75, 0x7f, v9
	s_and_b32 s19, s19, 0x180
	v_or_b32_e32 v8, s19, v75
	v_lshlrev_b32_e32 v0, 2, v8
	s_ashr_i32 s35, s37, 6
	global_load_dword v1, v0, s[4:5] offset:2048
	s_nop 0
	global_load_dword v0, v0, s[4:5]
	s_or_b32 s4, s19, s14
	s_mul_hi_i32 s5, s17, 0x1400
	s_mulk_i32 s17, 0x1400
	v_or_b32_e32 v10, s4, v75
	s_add_u32 s4, s82, s17
	s_addc_u32 s5, s83, s5
	s_mul_hi_i32 s17, s15, 0x1400
	s_mulk_i32 s15, 0x1400
	s_add_u32 s14, s82, s15
	s_addc_u32 s15, s83, s17
	s_mul_hi_i32 s17, s16, 0x1400
	s_mulk_i32 s16, 0x1400
	s_add_u32 s16, s82, s16
	s_addc_u32 s17, s83, s17
	s_mul_hi_i32 s19, s18, 0x1400
	s_mulk_i32 s18, 0x1400
	s_add_u32 s18, s82, s18
	s_addc_u32 s19, s83, s19
	s_mul_hi_i32 s21, s20, 0x1400
	s_mulk_i32 s20, 0x1400
	s_add_u32 s20, s82, s20
	s_addc_u32 s21, s83, s21
	s_mul_hi_i32 s23, s22, 0x1400
	s_mulk_i32 s22, 0x1400
	s_add_u32 s22, s82, s22
	s_addc_u32 s23, s83, s23
	s_mul_hi_i32 s25, s24, 0x1400
	s_mulk_i32 s24, 0x1400
	s_add_u32 s24, s82, s24
	s_addc_u32 s25, s83, s25
	s_mul_hi_i32 s27, s26, 0x1400
	s_mulk_i32 s26, 0x1400
	s_add_u32 s26, s82, s26
	s_addc_u32 s27, s83, s27
	s_mul_hi_i32 s45, s44, 0x1400
	s_mulk_i32 s44, 0x1400
	s_add_u32 s44, s82, s44
	s_addc_u32 s45, s83, s45
	s_mul_hi_i32 s47, s46, 0x1400
	s_mulk_i32 s46, 0x1400
	s_add_u32 s46, s82, s46
	s_addc_u32 s47, s83, s47
	s_mul_hi_i32 s49, s48, 0x1400
	s_mulk_i32 s48, 0x1400
	s_add_u32 s48, s82, s48
	s_addc_u32 s49, s83, s49
	s_mul_hi_i32 s51, s43, 0x1400
	s_mulk_i32 s43, 0x1400
	s_add_u32 s50, s82, s43
	s_addc_u32 s51, s83, s51
	s_mul_hi_i32 s43, s42, 0x1400
	s_mulk_i32 s42, 0x1400
	s_add_u32 s42, s82, s42
	s_addc_u32 s43, s83, s43
	s_mul_hi_i32 s53, s41, 0x1400
	s_mulk_i32 s41, 0x1400
	s_add_u32 s52, s82, s41
	s_addc_u32 s53, s83, s53
	s_mul_hi_i32 s41, s40, 0x1400
	s_mulk_i32 s40, 0x1400
	s_add_u32 s40, s82, s40
	s_addc_u32 s41, s83, s41
	s_mul_hi_i32 s55, s39, 0x1400
	s_mulk_i32 s39, 0x1400
	v_lshlrev_b32_e32 v2, 1, v10
	s_add_u32 s54, s82, s39
	s_addc_u32 s55, s83, s55
	global_load_ushort v3, v2, s[44:45]
	global_load_ushort v4, v2, s[46:47]
	global_load_ushort v5, v2, s[48:49]
	global_load_ushort v11, v2, s[50:51]
	global_load_ushort v6, v2, s[42:43]
	global_load_ushort v12, v2, s[52:53]
	global_load_ushort v7, v2, s[40:41]
	global_load_ushort v13, v2, s[54:55]
	global_load_ushort v14, v2, s[16:17]
	global_load_ushort v15, v2, s[18:19]
	global_load_ushort v16, v2, s[20:21]
	global_load_ushort v17, v2, s[24:25]
	global_load_ushort v18, v2, s[26:27]
	global_load_ushort v19, v2, s[22:23]
	global_load_ushort v20, v2, s[4:5]
	global_load_ushort v21, v2, s[14:15]
	v_lshlrev_b32_e32 v2, 1, v8
	global_load_ushort v22, v2, s[44:45] offset:3072
	global_load_ushort v23, v2, s[46:47] offset:3072
	global_load_ushort v24, v2, s[48:49] offset:3072
	global_load_ushort v25, v2, s[50:51] offset:3072
	global_load_ushort v26, v2, s[42:43] offset:3072
	global_load_ushort v27, v2, s[52:53] offset:3072
	global_load_ushort v28, v2, s[40:41] offset:3072
	global_load_ushort v29, v2, s[54:55] offset:3072
	global_load_ushort v30, v2, s[4:5] offset:3072
	global_load_ushort v31, v2, s[14:15] offset:3072
	global_load_ushort v32, v2, s[16:17] offset:3072
	global_load_ushort v33, v2, s[18:19] offset:3072
	global_load_ushort v34, v2, s[20:21] offset:3072
	global_load_ushort v35, v2, s[22:23] offset:3072
	global_load_ushort v36, v2, s[24:25] offset:3072
	global_load_ushort v37, v2, s[26:27] offset:3072
	s_lshl_b32 s20, s36, 5
	v_and_b32_e32 v78, 15, v9
	v_and_b32_e32 v77, 63, v9
	v_and_b32_e32 v81, 48, v9
	v_readlane_b32 s52, v254, 2
	v_add_u32_e32 v9, s29, v81
	v_readlane_b32 s53, v254, 3
	v_readlane_b32 s54, v254, 4
	s_waitcnt vmcnt(32)
	v_sub_f32_e32 v0, v1, v0
	v_mul_f32_e32 v0, 0x3fb8aa3b, v0
	v_exp_f32_e32 v0, v0
	v_readlane_b32 s55, v254, 5
	v_readlane_b32 s60, v254, 10
	v_readlane_b32 s61, v254, 11
	v_add_f32_e32 v0, 1.0, v0
	v_div_scale_f32 v1, s[4:5], v0, v0, 1.0
	v_rcp_f32_e32 v2, v1
	s_lshl_b32 s4, s36, 9
	s_add_i32 s4, s28, s4
	s_cmpk_lt_u32 s37, 0x80
	v_fma_f32 v38, -v1, v2, 1.0
	v_fmac_f32_e32 v2, v38, v2
	v_div_scale_f32 v38, vcc, 1.0, v0, 1.0
	v_mul_f32_e32 v39, v38, v2
	v_fma_f32 v40, -v1, v39, v38
	v_fmac_f32_e32 v39, v40, v2
	v_fma_f32 v1, -v1, v39, v38
	s_cselect_b64 s[14:15], -1, 0
	s_cmpk_gt_u32 s37, 0x7f
	v_div_fmas_f32 v1, v1, v2, v39
	s_cselect_b64 s[16:17], -1, 0
	s_andn2_b32 s37, s37, 63
	v_div_fixup_f32 v50, v1, v0, 1.0
	s_add_i32 s23, s31, s37
	s_cmp_lg_u32 s36, 1
	v_sub_f32_e32 v52, 1.0, v50
	s_cselect_b64 s[18:19], -1, 0
	s_cmp_eq_u32 s36, 2
	v_readlane_b32 s62, v254, 12
	v_readlane_b32 s63, v254, 13
	v_readlane_b32 s64, v254, 14
	v_readlane_b32 s65, v254, 15
	s_mov_b32 s22, 0
	v_mov_b32_e32 v76, 1.0
	v_mov_b32_e32 v51, v50
	v_mov_b32_e32 v53, v52
	v_lshlrev_b32_e32 v85, 1, v10
	v_lshlrev_b32_e32 v86, 1, v8
	v_readlane_b32 s56, v254, 6
	v_readlane_b32 s57, v254, 7
	v_readlane_b32 s58, v254, 8
	v_readlane_b32 s59, v254, 9
	v_readlane_b32 s66, v254, 16
	v_readlane_b32 s67, v254, 17
	s_waitcnt vmcnt(30)
	v_perm_b32 v4, v4, v3, s3
	s_waitcnt vmcnt(28)
	v_perm_b32 v5, v11, v5, s3
	v_lshlrev_b32_e32 v11, 2, v75
	s_waitcnt vmcnt(26)
	v_perm_b32 v6, v12, v6, s3
	v_mad_u32_u24 v12, v75, s30, v74
	s_waitcnt vmcnt(24)
	v_perm_b32 v7, v13, v7, s3
	v_mad_u32_u24 v13, v75, s30, 0
	s_waitcnt vmcnt(22)
	v_perm_b32 v1, v15, v14, s3
	v_lshl_or_b32 v14, s35, 4, v78
	v_mul_lo_u32 v14, v14, s30
	s_waitcnt vmcnt(19)
	v_perm_b32 v3, v18, v17, s3
	s_waitcnt vmcnt(18)
	v_perm_b32 v2, v19, v16, s3
	v_or_b32_e32 v16, 48, v77
	v_or_b32_e32 v17, 0x70, v77
	s_waitcnt vmcnt(16)
	v_perm_b32 v0, v21, v20, s3
	v_add_u32_e32 v14, 0, v14
	v_mul_u32_u24_e32 v15, 0x90, v78
	v_mul_u32_u24_e32 v16, 0x90, v16
	v_mul_u32_u24_e32 v17, 0x90, v17
	v_mov_b32_e32 v20, 0
	v_add_u32_e32 v79, s4, v11
	v_add_u32_e32 v80, s28, v11
	s_cselect_b64 s[4:5], -1, 0
	v_add_u32_e32 v82, s31, v11
	s_waitcnt vmcnt(14)
	v_perm_b32 v40, v23, v22, s3
	s_waitcnt vmcnt(12)
	v_perm_b32 v41, v25, v24, s3
	s_waitcnt vmcnt(10)
	v_perm_b32 v42, v27, v26, s3
	s_waitcnt vmcnt(8)
	v_perm_b32 v43, v29, v28, s3
	s_waitcnt vmcnt(6)
	v_perm_b32 v44, v31, v30, s3
	s_waitcnt vmcnt(4)
	v_perm_b32 v45, v33, v32, s3
	s_waitcnt vmcnt(2)
	v_perm_b32 v46, v35, v34, s3
	s_waitcnt vmcnt(0)
	v_perm_b32 v47, v37, v36, s3
	s_add_i32 s24, s38, 0xffffffb1
	v_add_u32_e32 v83, s20, v12
	v_add_u32_e32 v84, s20, v13
	v_add_u32_e32 v87, v14, v81
	v_add_u32_e32 v88, v9, v15
	v_add_u32_e32 v89, v9, v16
	v_add_u32_e32 v90, v9, v17
	v_mov_b32_e32 v21, v20
	v_mov_b32_e32 v22, v20
	v_mov_b32_e32 v23, v20
	v_mov_b32_e32 v8, v20
	v_mov_b32_e32 v9, v20
	v_mov_b32_e32 v10, v20
	v_mov_b32_e32 v11, v20
	v_mov_b32_e32 v12, v20
	v_mov_b32_e32 v13, v20
	v_mov_b32_e32 v14, v20
	v_mov_b32_e32 v15, v20
	v_mov_b32_e32 v16, v20
	v_mov_b32_e32 v17, v20
	v_mov_b32_e32 v18, v20
	v_mov_b32_e32 v19, v20
	v_mov_b32_e32 v36, v20
	v_mov_b32_e32 v37, v20
	v_mov_b32_e32 v38, v20
	v_mov_b32_e32 v39, v20
	v_mov_b32_e32 v28, v20
	v_mov_b32_e32 v29, v20
	v_mov_b32_e32 v30, v20
	v_mov_b32_e32 v31, v20
	v_mov_b32_e32 v24, v20
	v_mov_b32_e32 v25, v20
	v_mov_b32_e32 v26, v20
	v_mov_b32_e32 v27, v20
	v_mov_b32_e32 v32, v20
	v_mov_b32_e32 v33, v20
	v_mov_b32_e32 v34, v20
	v_mov_b32_e32 v35, v20
	s_branch .LBB0_330

.LBB0_330:
	s_cmpk_eq_i32 s22, 0x3c0
	s_cbranch_scc1 .Lp1_nopf
	s_add_i32 s40, s11, s22
	s_add_i32 s40, s40, 64
	s_add_i32 s41, s24, 15
	s_and_b64 s[42:43], s[12:13], exec
	s_cselect_b32 s40, s40, s41
	s_movk_i32 s42, 0x1400
	s_cselect_b32 s42, s42, 0xffffec00
	s_mul_hi_i32 s41, s40, 0x1400
	s_mulk_i32 s40, 0x1400
	s_add_u32 s40, s82, s40
	s_addc_u32 s41, s83, s41
	s_ashr_i32 s43, s42, 31
	global_load_ushort v206, v85, s[40:41]
	global_load_ushort v222, v86, s[40:41] offset:3072
	s_add_u32 s40, s40, s42
	s_addc_u32 s41, s41, s43
	global_load_ushort v207, v85, s[40:41]
	global_load_ushort v223, v86, s[40:41] offset:3072
	s_add_u32 s40, s40, s42
	s_addc_u32 s41, s41, s43
	global_load_ushort v208, v85, s[40:41]
	global_load_ushort v224, v86, s[40:41] offset:3072
	s_add_u32 s40, s40, s42
	s_addc_u32 s41, s41, s43
	global_load_ushort v209, v85, s[40:41]
	global_load_ushort v225, v86, s[40:41] offset:3072
	s_add_u32 s40, s40, s42
	s_addc_u32 s41, s41, s43
	global_load_ushort v210, v85, s[40:41]
	global_load_ushort v226, v86, s[40:41] offset:3072
	s_add_u32 s40, s40, s42
	s_addc_u32 s41, s41, s43
	global_load_ushort v211, v85, s[40:41]
	global_load_ushort v227, v86, s[40:41] offset:3072
	s_add_u32 s40, s40, s42
	s_addc_u32 s41, s41, s43
	global_load_ushort v212, v85, s[40:41]
	global_load_ushort v228, v86, s[40:41] offset:3072
	s_add_u32 s40, s40, s42
	s_addc_u32 s41, s41, s43
	global_load_ushort v213, v85, s[40:41]
	global_load_ushort v229, v86, s[40:41] offset:3072
	s_add_u32 s40, s40, s42
	s_addc_u32 s41, s41, s43
	global_load_ushort v214, v85, s[40:41]
	global_load_ushort v230, v86, s[40:41] offset:3072
	s_add_u32 s40, s40, s42
	s_addc_u32 s41, s41, s43
	global_load_ushort v215, v85, s[40:41]
	global_load_ushort v231, v86, s[40:41] offset:3072
	s_add_u32 s40, s40, s42
	s_addc_u32 s41, s41, s43
	global_load_ushort v216, v85, s[40:41]
	global_load_ushort v232, v86, s[40:41] offset:3072
	s_add_u32 s40, s40, s42
	s_addc_u32 s41, s41, s43
	global_load_ushort v217, v85, s[40:41]
	global_load_ushort v233, v86, s[40:41] offset:3072
	s_add_u32 s40, s40, s42
	s_addc_u32 s41, s41, s43
	global_load_ushort v218, v85, s[40:41]
	global_load_ushort v234, v86, s[40:41] offset:3072
	s_add_u32 s40, s40, s42
	s_addc_u32 s41, s41, s43
	global_load_ushort v219, v85, s[40:41]
	global_load_ushort v235, v86, s[40:41] offset:3072
	s_add_u32 s40, s40, s42
	s_addc_u32 s41, s41, s43
	global_load_ushort v220, v85, s[40:41]
	global_load_ushort v236, v86, s[40:41] offset:3072
	s_add_u32 s40, s40, s42
	s_addc_u32 s41, s41, s43
	global_load_ushort v221, v85, s[40:41]
	global_load_ushort v237, v86, s[40:41] offset:3072

.LBB0_483:
	s_or_b64 exec, exec, s[8:9]
	s_ashr_i32 s49, s36, 6
	s_ashr_i32 s50, s36, 7
	s_and_b64 s[8:9], s[4:5], exec
	s_cselect_b32 s8, s3, 0xb000000
	s_cselect_b32 s9, 0x200, s3
	s_add_u32 s8, s80, s8
	s_addc_u32 s10, s81, 0
	s_lshl_b32 s11, s7, 1
	s_add_u32 s37, s8, s11
	s_addc_u32 s38, s10, 0
	s_or_b32 s11, s7, s9
	s_ashr_i32 s7, s6, 31
	s_lshl_b64 s[8:9], s[6:7], 15
	s_add_u32 s8, s22, s8
	v_lshrrev_b32_e32 v2, 2, v32
	s_addc_u32 s9, s23, s9
	s_lshl_b32 s10, s49, 4
	v_and_b32_e32 v95, 12, v2
	v_or_b32_e32 v35, s10, v95
	v_lshlrev_b32_e32 v2, 7, v35
	s_waitcnt vmcnt(0)
	v_sub_f32_e32 v0, v0, v1
	v_ashrrev_i32_e32 v3, 31, v2
	v_and_b32_e32 v38, 15, v32
	v_mul_f32_e32 v0, 0x3fb8aa3b, v0
	v_lshl_add_u64 v[2:3], v[2:3], 1, s[8:9]
	v_lshlrev_b32_e32 v44, 1, v38
	v_exp_f32_e32 v0, v0
	v_lshl_add_u64 v[2:3], v[2:3], 0, v[44:45]
	global_load_ushort v4, v[2:3], off offset:256
	global_load_ushort v5, v[2:3], off
	global_load_ushort v6, v[2:3], off offset:768
	global_load_ushort v7, v[2:3], off offset:512
	global_load_ushort v8, v[2:3], off offset:288
	global_load_ushort v9, v[2:3], off offset:32
	global_load_ushort v10, v[2:3], off offset:800
	global_load_ushort v11, v[2:3], off offset:544
	global_load_ushort v12, v[2:3], off offset:320
	global_load_ushort v13, v[2:3], off offset:64
	global_load_ushort v14, v[2:3], off offset:832
	global_load_ushort v15, v[2:3], off offset:576
	global_load_ushort v16, v[2:3], off offset:352
	global_load_ushort v17, v[2:3], off offset:96
	global_load_ushort v18, v[2:3], off offset:864
	global_load_ushort v19, v[2:3], off offset:608
	global_load_ushort v20, v[2:3], off offset:384
	global_load_ushort v21, v[2:3], off offset:128
	global_load_ushort v22, v[2:3], off offset:896
	global_load_ushort v23, v[2:3], off offset:640
	global_load_ushort v36, v[2:3], off offset:416
	global_load_ushort v37, v[2:3], off offset:160
	global_load_ushort v39, v[2:3], off offset:928
	global_load_ushort v41, v[2:3], off offset:672
	global_load_ushort v42, v[2:3], off offset:448
	global_load_ushort v43, v[2:3], off offset:192
	global_load_ushort v47, v[2:3], off offset:960
	global_load_ushort v48, v[2:3], off offset:704
	global_load_ushort v49, v[2:3], off offset:480
	global_load_ushort v50, v[2:3], off offset:224
	global_load_ushort v51, v[2:3], off offset:992
	global_load_ushort v52, v[2:3], off offset:736
	s_lshl_b32 s6, s6, 7
	v_add_f32_e32 v0, 1.0, v0
	v_div_scale_f32 v1, s[8:9], v0, v0, 1.0
	s_lshl_b32 s51, s50, 4
	s_and_b32 s52, s6, 0xfffffc00
	s_or_b32 s53, s6, 0x3ff
	s_sub_i32 s8, s53, s51
	s_add_i32 s9, s51, s52
	s_and_b64 s[6:7], s[4:5], exec
	s_cselect_b32 s6, s9, s8
	s_mul_hi_i32 s7, s6, 0x1400
	s_mulk_i32 s6, 0x1400
	s_add_u32 s6, s82, s6
	s_addc_u32 s7, s83, s7
	s_or_b32 s8, s51, 1
	v_or_b32_e32 v40, s11, v33
	s_sub_i32 s11, s53, s8
	s_add_i32 s12, s8, s52
	s_and_b64 s[8:9], s[4:5], exec
	s_cselect_b32 s8, s12, s11
	s_mul_hi_i32 s9, s8, 0x1400
	s_mulk_i32 s8, 0x1400
	s_add_u32 s8, s82, s8
	s_addc_u32 s9, s83, s9
	s_or_b32 s11, s51, 2
	s_sub_i32 s14, s53, s11
	s_add_i32 s11, s11, s52
	s_and_b64 s[12:13], s[4:5], exec
	s_cselect_b32 s11, s11, s14
	s_mul_hi_i32 s13, s11, 0x1400
	s_mulk_i32 s11, 0x1400
	s_add_u32 s12, s82, s11
	s_addc_u32 s13, s83, s13
	s_or_b32 s11, s51, 3
	s_sub_i32 s16, s53, s11
	s_add_i32 s11, s11, s52
	s_and_b64 s[14:15], s[4:5], exec
	s_cselect_b32 s11, s11, s16
	s_mul_hi_i32 s15, s11, 0x1400
	s_mulk_i32 s11, 0x1400
	s_add_u32 s14, s82, s11
	s_addc_u32 s15, s83, s15
	s_or_b32 s11, s51, 4
	s_sub_i32 s18, s53, s11
	s_add_i32 s11, s11, s52
	s_and_b64 s[16:17], s[4:5], exec
	s_cselect_b32 s11, s11, s18
	s_mul_hi_i32 s17, s11, 0x1400
	s_mulk_i32 s11, 0x1400
	s_add_u32 s16, s82, s11
	s_addc_u32 s17, s83, s17
	s_or_b32 s11, s51, 5
	s_sub_i32 s24, s53, s11
	s_add_i32 s11, s11, s52
	s_and_b64 s[18:19], s[4:5], exec
	s_cselect_b32 s11, s11, s24
	s_mul_hi_i32 s19, s11, 0x1400
	s_mulk_i32 s11, 0x1400
	s_add_u32 s18, s82, s11
	s_addc_u32 s19, s83, s19
	s_or_b32 s11, s51, 6
	s_sub_i32 s26, s53, s11
	s_add_i32 s11, s11, s52
	s_and_b64 s[24:25], s[4:5], exec
	s_cselect_b32 s11, s11, s26
	s_mul_hi_i32 s25, s11, 0x1400
	s_mulk_i32 s11, 0x1400
	s_add_u32 s24, s82, s11
	s_addc_u32 s25, s83, s25
	s_or_b32 s11, s51, 7
	s_sub_i32 s28, s53, s11
	s_add_i32 s11, s11, s52
	s_and_b64 s[26:27], s[4:5], exec
	s_cselect_b32 s11, s11, s28
	s_mul_hi_i32 s27, s11, 0x1400
	s_mulk_i32 s11, 0x1400
	s_add_u32 s26, s82, s11
	s_addc_u32 s27, s83, s27
	s_or_b32 s11, s51, 8
	s_sub_i32 s30, s53, s11
	s_add_i32 s11, s11, s52
	s_and_b64 s[28:29], s[4:5], exec
	s_cselect_b32 s11, s11, s30
	s_mul_hi_i32 s29, s11, 0x1400
	s_mulk_i32 s11, 0x1400
	s_add_u32 s28, s82, s11
	s_addc_u32 s29, s83, s29
	s_or_b32 s11, s51, 9
	s_sub_i32 s34, s53, s11
	s_add_i32 s11, s11, s52
	s_and_b64 s[30:31], s[4:5], exec
	s_cselect_b32 s11, s11, s34
	s_mul_hi_i32 s31, s11, 0x1400
	s_mulk_i32 s11, 0x1400
	v_rcp_f32_e32 v2, v1
	s_add_u32 s30, s82, s11
	s_addc_u32 s31, s83, s31
	s_or_b32 s11, s51, 10
	s_sub_i32 s39, s53, s11
	s_add_i32 s11, s11, s52
	s_and_b64 s[34:35], s[4:5], exec
	v_fma_f32 v24, -v1, v2, 1.0
	s_cselect_b32 s11, s11, s39
	v_div_scale_f32 v3, vcc, 1.0, v0, 1.0
	v_fmac_f32_e32 v2, v24, v2
	s_mul_hi_i32 s35, s11, 0x1400
	s_mulk_i32 s11, 0x1400
	v_mul_f32_e32 v24, v3, v2
	s_add_u32 s34, s82, s11
	v_fma_f32 v25, -v1, v24, v3
	s_addc_u32 s35, s83, s35
	s_or_b32 s11, s51, 11
	v_fmac_f32_e32 v24, v25, v2
	s_sub_i32 s39, s53, s11
	s_add_i32 s11, s11, s52
	v_fma_f32 v1, -v1, v24, v3
	s_and_b64 s[54:55], s[4:5], exec
	v_div_fmas_f32 v1, v1, v2, v24
	s_cselect_b32 s11, s11, s39
	v_div_fixup_f32 v46, v1, v0, 1.0
	s_waitcnt vmcnt(31)
	v_lshlrev_b32_e32 v1, 16, v4
	s_waitcnt vmcnt(30)
	v_lshlrev_b32_e32 v0, 16, v5
	s_waitcnt vmcnt(29)
	v_lshlrev_b32_e32 v3, 16, v6
	s_waitcnt vmcnt(28)
	v_lshlrev_b32_e32 v2, 16, v7
	v_lshl_add_u32 v96, v35, 1, s33
	s_mul_hi_i32 s39, s11, 0x1400
	s_mulk_i32 s11, 0x1400
	s_waitcnt vmcnt(27)
	v_lshlrev_b32_e32 v5, 16, v8
	s_waitcnt vmcnt(26)
	v_lshlrev_b32_e32 v4, 16, v9
	s_waitcnt vmcnt(25)
	v_lshlrev_b32_e32 v7, 16, v10
	s_waitcnt vmcnt(24)
	v_lshlrev_b32_e32 v6, 16, v11
	s_waitcnt vmcnt(23)
	v_lshlrev_b32_e32 v25, 16, v12
	s_waitcnt vmcnt(22)
	v_lshlrev_b32_e32 v24, 16, v13
	s_waitcnt vmcnt(11)
	v_lshlrev_b32_e32 v13, 16, v36
	s_waitcnt vmcnt(10)
	v_lshlrev_b32_e32 v12, 16, v37
	v_cvt_pk_bf16_f32 v36, v0, v1
	v_cvt_pk_bf16_f32 v37, v2, v3
	v_mad_u32_u24 v35, v38, s40, v96
	s_add_u32 s54, s82, s11
	v_lshlrev_b32_e32 v27, 16, v14
	v_lshlrev_b32_e32 v26, 16, v15
	ds_write_b64 v35, v[36:37]
	v_cvt_pk_bf16_f32 v36, v4, v5
	v_cvt_pk_bf16_f32 v37, v6, v7
	s_addc_u32 s55, s83, s39
	s_or_b32 s11, s51, 12
	v_lshlrev_b32_e32 v29, 16, v16
	v_lshlrev_b32_e32 v28, 16, v17
	v_lshlrev_b32_e32 v31, 16, v18
	v_lshlrev_b32_e32 v30, 16, v19
	ds_write_b64 v35, v[36:37] offset:4352
	v_cvt_pk_bf16_f32 v36, v24, v25
	v_cvt_pk_bf16_f32 v37, v26, v27
	s_sub_i32 s39, s53, s11
	s_add_i32 s11, s11, s52
	v_lshlrev_b32_e32 v9, 16, v20
	v_lshlrev_b32_e32 v8, 16, v21
	v_lshlrev_b32_e32 v11, 16, v22
	v_lshlrev_b32_e32 v10, 16, v23
	ds_write_b64 v35, v[36:37] offset:8704
	v_cvt_pk_bf16_f32 v36, v28, v29
	v_cvt_pk_bf16_f32 v37, v30, v31
	s_and_b64 s[56:57], s[4:5], exec
	s_waitcnt vmcnt(9)
	v_lshlrev_b32_e32 v15, 16, v39
	s_waitcnt vmcnt(8)
	v_lshlrev_b32_e32 v14, 16, v41
	ds_write_b64 v35, v[36:37] offset:13056
	v_cvt_pk_bf16_f32 v36, v8, v9
	v_cvt_pk_bf16_f32 v37, v10, v11
	s_cselect_b32 s11, s11, s39
	s_waitcnt vmcnt(7)
	v_lshlrev_b32_e32 v17, 16, v42
	s_waitcnt vmcnt(6)
	v_lshlrev_b32_e32 v16, 16, v43
	s_waitcnt vmcnt(5)
	v_lshlrev_b32_e32 v19, 16, v47
	s_waitcnt vmcnt(4)
	v_lshlrev_b32_e32 v18, 16, v48
	ds_write_b64 v35, v[36:37] offset:17408
	v_cvt_pk_bf16_f32 v36, v12, v13
	v_cvt_pk_bf16_f32 v37, v14, v15
	s_mul_hi_i32 s39, s11, 0x1400
	s_mulk_i32 s11, 0x1400
	s_waitcnt vmcnt(3)
	v_lshlrev_b32_e32 v21, 16, v49
	s_waitcnt vmcnt(2)
	v_lshlrev_b32_e32 v20, 16, v50
	s_waitcnt vmcnt(1)
	v_lshlrev_b32_e32 v23, 16, v51
	s_waitcnt vmcnt(0)
	v_lshlrev_b32_e32 v22, 16, v52
	ds_write_b64 v35, v[36:37] offset:21760
	v_cvt_pk_bf16_f32 v36, v16, v17
	v_cvt_pk_bf16_f32 v37, v18, v19
	s_add_u32 s56, s82, s11
	ds_write_b64 v35, v[36:37] offset:26112
	v_cvt_pk_bf16_f32 v36, v20, v21
	v_cvt_pk_bf16_f32 v37, v22, v23
	s_addc_u32 s57, s83, s39
	s_or_b32 s11, s51, 13
	ds_write_b64 v35, v[36:37] offset:30464
	v_lshlrev_b32_e32 v98, 1, v34
	s_sub_i32 s39, s53, s11
	s_add_i32 s11, s11, s52
	global_load_ushort v99, v98, s[6:7]
	global_load_ushort v34, v98, s[6:7] offset:3072
	global_load_ushort v100, v98, s[8:9]
	global_load_ushort v36, v98, s[8:9] offset:3072
	global_load_ushort v101, v98, s[12:13]
	global_load_ushort v37, v98, s[12:13] offset:3072
	global_load_ushort v102, v98, s[14:15]
	global_load_ushort v41, v98, s[14:15] offset:3072
	global_load_ushort v103, v98, s[16:17]
	global_load_ushort v42, v98, s[16:17] offset:3072
	global_load_ushort v104, v98, s[18:19]
	global_load_ushort v43, v98, s[18:19] offset:3072
	global_load_ushort v105, v98, s[24:25]
	global_load_ushort v52, v98, s[24:25] offset:3072
	global_load_ushort v117, v98, s[26:27]
	global_load_ushort v54, v98, s[26:27] offset:3072
	global_load_ushort v134, v98, s[28:29]
	global_load_ushort v55, v98, s[28:29] offset:3072
	global_load_ushort v136, v98, s[30:31]
	global_load_ushort v56, v98, s[30:31] offset:3072
	global_load_ushort v137, v98, s[34:35]
	global_load_ushort v57, v98, s[34:35] offset:3072
	global_load_ushort v140, v98, s[54:55]
	global_load_ushort v58, v98, s[54:55] offset:3072
	s_and_b64 s[60:61], s[4:5], exec
	s_cselect_b32 s11, s11, s39
	s_mul_hi_i32 s39, s11, 0x1400
	s_mulk_i32 s11, 0x1400
	s_add_u32 s60, s82, s11
	s_addc_u32 s61, s83, s39
	s_or_b32 s11, s51, 14
	s_sub_i32 s39, s53, s11
	s_add_i32 s11, s11, s52
	s_and_b64 s[62:63], s[4:5], exec
	s_cselect_b32 s11, s11, s39
	s_mul_hi_i32 s39, s11, 0x1400
	s_mulk_i32 s11, 0x1400
	s_add_u32 s62, s82, s11
	s_addc_u32 s63, s83, s39
	s_or_b32 s11, s51, 15
	s_sub_i32 s39, s53, s11
	s_add_i32 s11, s11, s52
	s_and_b64 s[64:65], s[4:5], exec
	s_cselect_b32 s11, s11, s39
	s_mul_hi_i32 s39, s11, 0x1400
	s_mulk_i32 s11, 0x1400
	s_add_u32 s64, s82, s11
	v_lshlrev_b32_e32 v35, 1, v40
	s_addc_u32 s65, s83, s39
	global_load_ushort v147, v98, s[56:57]
	global_load_ushort v59, v98, s[56:57] offset:3072
	global_load_ushort v150, v98, s[60:61]
	global_load_ushort v60, v98, s[60:61] offset:3072
	global_load_ushort v152, v98, s[62:63]
	global_load_ushort v61, v98, s[62:63] offset:3072
	global_load_ushort v154, v98, s[64:65]
	global_load_ushort v62, v98, s[64:65] offset:3072
	global_load_ushort v106, v35, s[6:7]
	global_load_ushort v109, v35, s[8:9]
	global_load_ushort v115, v35, s[12:13]
	global_load_ushort v121, v35, s[14:15]
	global_load_ushort v129, v35, s[16:17]
	global_load_ushort v133, v35, s[18:19]
	global_load_ushort v135, v35, s[24:25]
	global_load_ushort v138, v35, s[26:27]
	global_load_ushort v139, v35, s[28:29]
	global_load_ushort v141, v35, s[30:31]
	global_load_ushort v142, v35, s[34:35]
	global_load_ushort v143, v35, s[54:55]
	global_load_ushort v149, v35, s[56:57]
	global_load_ushort v151, v35, s[60:61]
	global_load_ushort v153, v35, s[62:63]
	global_load_ushort v155, v35, s[64:65]
	s_lshl_b32 s6, s50, 9
	s_add_i32 s6, s41, s6
	s_lshl_b32 s54, s50, 5
	v_lshlrev_b32_e32 v35, 2, v33
	s_cmpk_lt_u32 s36, 0x80
	v_add_u32_e32 v107, s6, v35
	s_cselect_b64 s[6:7], -1, 0
	s_cmpk_gt_u32 s36, 0x7f
	s_cselect_b64 s[24:25], -1, 0
	s_cmp_eq_u32 s50, 1
	s_cselect_b64 s[26:27], -1, 0
	s_cmp_lg_u32 s50, 1
	s_cselect_b64 s[28:29], -1, 0
	s_cmp_eq_u32 s50, 2
	s_cselect_b64 s[8:9], -1, 0
	s_cmp_eq_u32 s50, 3
	v_lshl_add_u32 v110, v33, 1, 0
	s_cselect_b64 s[30:31], -1, 0
	s_cmp_lt_i32 s49, 10
	v_mad_u32_u24 v111, v33, s44, v110
	s_cselect_b64 s[34:35], -1, 0
	s_ashr_i32 s11, s10, 31
	v_mad_u32_u24 v63, v33, s43, v94
	v_mad_i32_i24 v64, v33, s45, v111
	v_or_b32_e32 v33, s10, v38
	s_lshl_b64 s[10:11], s[10:11], 1
	v_and_b32_e32 v53, 63, v32
	v_and_b32_e32 v112, 48, v32
	v_mul_lo_u32 v32, v33, s43
	s_add_u32 s10, s37, s10
	v_add_u32_e32 v66, s42, v32
	s_addc_u32 s11, s38, s11
	v_add_u32_e32 v67, 0, v32
	s_andn2_b32 s36, s36, 63
	v_or_b32_e32 v32, 48, v53
	s_add_i32 s56, s46, s36
	v_mul_u32_u24_e32 v68, 0x90, v32
	v_or_b32_e32 v32, 0x70, v53
	v_mul_u32_u24_e32 v53, 0x90, v32
	v_or_b32_e32 v32, 1, v95
	s_and_b64 s[18:19], s[4:5], exec
	v_or_b32_e32 v39, 16, v38
	v_mul_lo_u32 v47, v33, s40
	v_cmp_gt_u32_e64 s[12:13], v38, v32
	v_or_b32_e32 v32, 2, v95
	s_cselect_b32 s57, 10, 9
	s_lshl_b32 s18, s49, 5
	v_sub_f32_e32 v48, 1.0, v46
	s_mul_i32 s55, s50, 0x1100
	v_add_u32_e32 v65, s33, v47
	v_add_u32_e32 v113, 0, v112
	v_add_u32_e32 v114, s1, v112
	v_add_u32_e32 v116, s42, v112
	v_cmp_gt_u32_e64 s[14:15], v38, v32
	v_or_b32_e32 v32, 3, v95
	v_mul_u32_u24_e32 v69, 0x90, v39
	s_add_i32 s18, s1, s18
	s_mul_i32 s58, s49, 0x1100
	s_mov_b32 s59, 0
	v_mul_u32_u24_e32 v97, 0x110, v38
	v_add_u32_e32 v108, s41, v35
	v_lshl_add_u64 v[50:51], s[10:11], 0, v[44:45]
	v_mul_u32_u24_e32 v118, 0x90, v38
	v_add_u32_e32 v119, s46, v35
	v_mad_u32_u24 v120, v38, s40, v113
	v_cmp_gt_u32_e64 s[10:11], v38, v95
	v_cmp_gt_u32_e64 s[16:17], v38, v32
	v_mov_b32_e32 v47, v46
	v_mov_b32_e32 v49, v48
	s_waitcnt vmcnt(44)
	v_perm_b32 v32, v36, v34, s47
	s_waitcnt vmcnt(40)
	v_perm_b32 v33, v41, v37, s47
	s_waitcnt vmcnt(36)
	v_perm_b32 v34, v43, v42, s47
	s_waitcnt vmcnt(32)
	v_perm_b32 v35, v54, v52, s47
	s_waitcnt vmcnt(28)
	v_perm_b32 v36, v56, v55, s47
	s_waitcnt vmcnt(24)
	v_perm_b32 v37, v58, v57, s47
	s_waitcnt vmcnt(20)
	v_perm_b32 v38, v60, v59, s47
	s_waitcnt vmcnt(16)
	v_perm_b32 v39, v62, v61, s47
	v_add_u32_e32 v122, s18, v44
	s_add_i32 s58, s58, 0x8800
	v_add_u32_e32 v123, s54, v63
	v_add_u32_e32 v124, s55, v64
	v_lshlrev_b32_e32 v125, 1, v40
	v_add_u32_e32 v126, v65, v112
	v_add_u32_e32 v127, v66, v112
	v_add_u32_e32 v128, v114, v69
	v_add_u32_e32 v130, v67, v112
	v_add_u32_e32 v131, v116, v68
	v_add_u32_e32 v132, v116, v53
	s_waitcnt vmcnt(0)
	s_branch .LBB0_485

.LBB0_485:
	s_cmp_eq_u32 s59, 15
	s_cbranch_scc1 .Lp2_nopf
	s_lshl_b32 s98, s59, 6
	s_add_i32 s98, s98, 64
	s_add_i32 s98, s98, s51
	s_sub_i32 s99, s53, s98
	s_add_i32 s98, s98, s52
	s_and_b64 s[100:101], s[4:5], exec
	s_cselect_b32 s98, s98, s99
	s_movk_i32 s100, 0x1400
	s_cselect_b32 s100, s100, 0xffffec00
	s_mul_hi_i32 s99, s98, 0x1400
	s_mulk_i32 s98, 0x1400
	s_add_u32 s98, s82, s98
	s_addc_u32 s99, s83, s99
	s_ashr_i32 s101, s100, 31
	global_load_ushort v190, v125, s[98:99]
	global_load_ushort v206, v98, s[98:99]
	global_load_ushort v222, v98, s[98:99] offset:3072
	s_add_u32 s98, s98, s100
	s_addc_u32 s99, s99, s101
	global_load_ushort v191, v125, s[98:99]
	global_load_ushort v207, v98, s[98:99]
	global_load_ushort v223, v98, s[98:99] offset:3072
	s_add_u32 s98, s98, s100
	s_addc_u32 s99, s99, s101
	global_load_ushort v192, v125, s[98:99]
	global_load_ushort v208, v98, s[98:99]
	global_load_ushort v224, v98, s[98:99] offset:3072
	s_add_u32 s98, s98, s100
	s_addc_u32 s99, s99, s101
	global_load_ushort v193, v125, s[98:99]
	global_load_ushort v209, v98, s[98:99]
	global_load_ushort v225, v98, s[98:99] offset:3072
	s_add_u32 s98, s98, s100
	s_addc_u32 s99, s99, s101
	global_load_ushort v194, v125, s[98:99]
	global_load_ushort v210, v98, s[98:99]
	global_load_ushort v226, v98, s[98:99] offset:3072
	s_add_u32 s98, s98, s100
	s_addc_u32 s99, s99, s101
	global_load_ushort v195, v125, s[98:99]
	global_load_ushort v211, v98, s[98:99]
	global_load_ushort v227, v98, s[98:99] offset:3072
	s_add_u32 s98, s98, s100
	s_addc_u32 s99, s99, s101
	global_load_ushort v196, v125, s[98:99]
	global_load_ushort v212, v98, s[98:99]
	global_load_ushort v228, v98, s[98:99] offset:3072
	s_add_u32 s98, s98, s100
	s_addc_u32 s99, s99, s101
	global_load_ushort v197, v125, s[98:99]
	global_load_ushort v213, v98, s[98:99]
	global_load_ushort v229, v98, s[98:99] offset:3072
	s_add_u32 s98, s98, s100
	s_addc_u32 s99, s99, s101
	global_load_ushort v198, v125, s[98:99]
	global_load_ushort v214, v98, s[98:99]
	global_load_ushort v230, v98, s[98:99] offset:3072
	s_add_u32 s98, s98, s100
	s_addc_u32 s99, s99, s101
	global_load_ushort v199, v125, s[98:99]
	global_load_ushort v215, v98, s[98:99]
	global_load_ushort v231, v98, s[98:99] offset:3072
	s_add_u32 s98, s98, s100
	s_addc_u32 s99, s99, s101
	global_load_ushort v200, v125, s[98:99]
	global_load_ushort v216, v98, s[98:99]
	global_load_ushort v232, v98, s[98:99] offset:3072
	s_add_u32 s98, s98, s100
	s_addc_u32 s99, s99, s101
	global_load_ushort v201, v125, s[98:99]
	global_load_ushort v217, v98, s[98:99]
	global_load_ushort v233, v98, s[98:99] offset:3072
	s_add_u32 s98, s98, s100
	s_addc_u32 s99, s99, s101
	global_load_ushort v202, v125, s[98:99]
	global_load_ushort v218, v98, s[98:99]
	global_load_ushort v234, v98, s[98:99] offset:3072
	s_add_u32 s98, s98, s100
	s_addc_u32 s99, s99, s101
	global_load_ushort v203, v125, s[98:99]
	global_load_ushort v219, v98, s[98:99]
	global_load_ushort v235, v98, s[98:99] offset:3072
	s_add_u32 s98, s98, s100
	s_addc_u32 s99, s99, s101
	global_load_ushort v204, v125, s[98:99]
	global_load_ushort v220, v98, s[98:99]
	global_load_ushort v236, v98, s[98:99] offset:3072
	s_add_u32 s98, s98, s100
	s_addc_u32 s99, s99, s101
	global_load_ushort v205, v125, s[98:99]
	global_load_ushort v221, v98, s[98:99]
	global_load_ushort v237, v98, s[98:99] offset:3072
